# nsa top-16 selection: the wave's four queries searched together (interleaved threshold search, 2 VALU->SALU round trips per bit instead of 8)
# baseline (speedup 1.0000x reference)
.LBB0_1456:
	v_mov_b32_e32 v0, v99
	ds_read2st64_b32 v[56:57], v0 offset1:1
	v_mov_b32_e32 v59, v1
	s_waitcnt lgkmcnt(0)
	v_mov_b32_e32 v0, v56
	v_mov_b32_e32 v58, v57
	v_lshlrev_b64 v[56:57], 7, v[0:1]
	v_lshlrev_b64 v[58:59], 7, v[58:59]
	v_cndmask_b32_e64 v57, v57, 39, s[14:15]
	v_cndmask_b32_e64 v56, v56, v133, s[14:15]
	v_cndmask_b32_e64 v55, v58, v133, s[16:17]
	v_cndmask_b32_e64 v0, v59, 39, s[16:17]
	v_lshl_add_u64 v[56:57], v[56:57], 0, v[52:53]
	v_or_b32_e32 v55, v55, v54
	v_cndmask_b32_e64 v183, v57, 0, s[18:19]
	v_cndmask_b32_e64 v182, v56, 0, s[18:19]
	v_cndmask_b32_e64 v185, v0, 0, s[20:21]
	v_cndmask_b32_e64 v184, v55, 0, s[20:21]
	v_add_u32_e32 v0, 0x200, v99
	ds_read2st64_b32 v[56:57], v0 offset1:1
	v_mov_b32_e32 v59, v1
	s_waitcnt lgkmcnt(0)
	v_mov_b32_e32 v0, v56
	v_mov_b32_e32 v58, v57
	v_lshlrev_b64 v[56:57], 7, v[0:1]
	v_lshlrev_b64 v[58:59], 7, v[58:59]
	v_cndmask_b32_e64 v57, v57, 39, s[14:15]
	v_cndmask_b32_e64 v56, v56, v133, s[14:15]
	v_cndmask_b32_e64 v55, v58, v133, s[16:17]
	v_cndmask_b32_e64 v0, v59, 39, s[16:17]
	v_lshl_add_u64 v[56:57], v[56:57], 0, v[52:53]
	v_or_b32_e32 v55, v55, v54
	v_cndmask_b32_e64 v187, v57, 0, s[18:19]
	v_cndmask_b32_e64 v186, v56, 0, s[18:19]
	v_cndmask_b32_e64 v189, v0, 0, s[20:21]
	v_cndmask_b32_e64 v188, v55, 0, s[20:21]
	v_add_u32_e32 v0, 0x400, v99
	ds_read2st64_b32 v[56:57], v0 offset1:1
	v_mov_b32_e32 v59, v1
	s_waitcnt lgkmcnt(0)
	v_mov_b32_e32 v0, v56
	v_mov_b32_e32 v58, v57
	v_lshlrev_b64 v[56:57], 7, v[0:1]
	v_lshlrev_b64 v[58:59], 7, v[58:59]
	v_cndmask_b32_e64 v57, v57, 39, s[14:15]
	v_cndmask_b32_e64 v56, v56, v133, s[14:15]
	v_cndmask_b32_e64 v55, v58, v133, s[16:17]
	v_cndmask_b32_e64 v0, v59, 39, s[16:17]
	v_lshl_add_u64 v[56:57], v[56:57], 0, v[52:53]
	v_or_b32_e32 v55, v55, v54
	v_cndmask_b32_e64 v191, v57, 0, s[18:19]
	v_cndmask_b32_e64 v190, v56, 0, s[18:19]
	v_cndmask_b32_e64 v193, v0, 0, s[20:21]
	v_cndmask_b32_e64 v192, v55, 0, s[20:21]
	v_add_u32_e32 v0, 0x600, v99
	ds_read2st64_b32 v[56:57], v0 offset1:1
	v_mov_b32_e32 v59, v1
	s_waitcnt lgkmcnt(0)
	v_mov_b32_e32 v0, v56
	v_mov_b32_e32 v58, v57
	v_lshlrev_b64 v[56:57], 7, v[0:1]
	v_lshlrev_b64 v[58:59], 7, v[58:59]
	v_cndmask_b32_e64 v57, v57, 39, s[14:15]
	v_cndmask_b32_e64 v56, v56, v133, s[14:15]
	v_cndmask_b32_e64 v55, v58, v133, s[16:17]
	v_cndmask_b32_e64 v0, v59, 39, s[16:17]
	v_lshl_add_u64 v[56:57], v[56:57], 0, v[52:53]
	v_or_b32_e32 v55, v55, v54
	v_cndmask_b32_e64 v195, v57, 0, s[18:19]
	v_cndmask_b32_e64 v194, v56, 0, s[18:19]
	v_cndmask_b32_e64 v197, v0, 0, s[20:21]
	v_cndmask_b32_e64 v196, v55, 0, s[20:21]
	s_mov_b64 s[78:79], 0
	s_mov_b64 s[80:81], 0
	s_mov_b64 s[82:83], 0
	s_mov_b64 s[84:85], 0
	s_mov_b32 s73, 39
	s_mov_b32 s77, 0
.Ltk4_loop:
	s_lshl_b64 s[86:87], 1, s73
	s_or_b64 s[74:75], s[86:87], s[78:79]
	v_cmp_le_u64_e64 s[88:89], s[74:75], v[182:183]
	v_cmp_le_u64_e64 s[98:99], s[74:75], v[184:185]
	s_or_b64 s[74:75], s[86:87], s[80:81]
	v_cmp_le_u64_e64 s[68:69], s[74:75], v[186:187]
	v_cmp_le_u64_e64 s[70:71], s[74:75], v[188:189]
	s_bcnt1_i32_b64 s88, s[88:89]
	s_bcnt1_i32_b64 s98, s[98:99]
	s_add_i32 s76, s88, s98
	s_or_b64 s[74:75], s[86:87], s[78:79]
	s_cmp_gt_u32 s76, 15
	s_cselect_b32 s79, s75, s79
	s_cselect_b32 s78, s74, s78
	s_cmp_eq_u32 s76, 16
	s_cselect_b32 s76, 1, 0
	s_or_b32 s77, s77, s76
	s_bcnt1_i32_b64 s68, s[68:69]
	s_bcnt1_i32_b64 s70, s[70:71]
	s_add_i32 s76, s68, s70
	s_or_b64 s[74:75], s[86:87], s[80:81]
	s_cmp_gt_u32 s76, 15
	s_cselect_b32 s81, s75, s81
	s_cselect_b32 s80, s74, s80
	s_cmp_eq_u32 s76, 16
	s_cselect_b32 s76, 2, 0
	s_or_b32 s77, s77, s76
	s_or_b64 s[74:75], s[86:87], s[82:83]
	v_cmp_le_u64_e64 s[88:89], s[74:75], v[190:191]
	v_cmp_le_u64_e64 s[98:99], s[74:75], v[192:193]
	s_or_b64 s[74:75], s[86:87], s[84:85]
	v_cmp_le_u64_e64 s[68:69], s[74:75], v[194:195]
	v_cmp_le_u64_e64 s[70:71], s[74:75], v[196:197]
	s_bcnt1_i32_b64 s88, s[88:89]
	s_bcnt1_i32_b64 s98, s[98:99]
	s_add_i32 s76, s88, s98
	s_or_b64 s[74:75], s[86:87], s[82:83]
	s_cmp_gt_u32 s76, 15
	s_cselect_b32 s83, s75, s83
	s_cselect_b32 s82, s74, s82
	s_cmp_eq_u32 s76, 16
	s_cselect_b32 s76, 4, 0
	s_or_b32 s77, s77, s76
	s_bcnt1_i32_b64 s68, s[68:69]
	s_bcnt1_i32_b64 s70, s[70:71]
	s_add_i32 s76, s68, s70
	s_or_b64 s[74:75], s[86:87], s[84:85]
	s_cmp_gt_u32 s76, 15
	s_cselect_b32 s85, s75, s85
	s_cselect_b32 s84, s74, s84
	s_cmp_eq_u32 s76, 16
	s_cselect_b32 s76, 8, 0
	s_or_b32 s77, s77, s76
	s_cmp_eq_u32 s77, 15
	s_cbranch_scc1 .Ltk4_done
	s_add_i32 s73, s73, -1
	s_cmp_lt_i32 s73, 0
	s_cbranch_scc0 .Ltk4_loop
.Ltk4_done:
	s_cmp_eq_u64 s[78:79], 0
	s_cselect_b32 s78, 1, s78
	v_cmp_le_u64_e64 s[74:75], s[78:79], v[182:183]
	v_cmp_le_u64_e32 vcc, s[78:79], v[184:185]
	s_and_saveexec_b64 s[68:69], s[12:13]
	v_mov_b32_e32 v0, v98
	v_mov_b32_e32 v56, s74
	v_mov_b32_e32 v57, s75
	v_mov_b32_e32 v58, vcc_lo
	v_mov_b32_e32 v59, vcc_hi
	ds_write_b128 v0, v[56:59] offset:2048
	s_or_b64 exec, exec, s[68:69]
	s_cmp_eq_u64 s[80:81], 0
	s_cselect_b32 s80, 1, s80
	v_cmp_le_u64_e64 s[74:75], s[80:81], v[186:187]
	v_cmp_le_u64_e32 vcc, s[80:81], v[188:189]
	s_and_saveexec_b64 s[68:69], s[12:13]
	v_add_u32_e32 v0, 0x10, v98
	v_mov_b32_e32 v56, s74
	v_mov_b32_e32 v57, s75
	v_mov_b32_e32 v58, vcc_lo
	v_mov_b32_e32 v59, vcc_hi
	ds_write_b128 v0, v[56:59] offset:2048
	s_or_b64 exec, exec, s[68:69]
	s_cmp_eq_u64 s[82:83], 0
	s_cselect_b32 s82, 1, s82
	v_cmp_le_u64_e64 s[74:75], s[82:83], v[190:191]
	v_cmp_le_u64_e32 vcc, s[82:83], v[192:193]
	s_and_saveexec_b64 s[68:69], s[12:13]
	v_add_u32_e32 v0, 0x20, v98
	v_mov_b32_e32 v56, s74
	v_mov_b32_e32 v57, s75
	v_mov_b32_e32 v58, vcc_lo
	v_mov_b32_e32 v59, vcc_hi
	ds_write_b128 v0, v[56:59] offset:2048
	s_or_b64 exec, exec, s[68:69]
	s_cmp_eq_u64 s[84:85], 0
	s_cselect_b32 s84, 1, s84
	v_cmp_le_u64_e64 s[74:75], s[84:85], v[194:195]
	v_cmp_le_u64_e32 vcc, s[84:85], v[196:197]
	s_and_saveexec_b64 s[68:69], s[12:13]
	v_add_u32_e32 v0, 0x30, v98
	v_mov_b32_e32 v56, s74
	v_mov_b32_e32 v57, s75
	v_mov_b32_e32 v58, vcc_lo
	v_mov_b32_e32 v59, vcc_hi
	ds_write_b128 v0, v[56:59] offset:2048
	s_or_b64 exec, exec, s[68:69]
